# v54 plus first GEMM K-iteration peeled with C=0 MFMAs so the 128-register accumulator zeroing pass per unit is gone
# speedup vs baseline: 1.0065x; 1.0065x over previous
; #define PG8_STAGE(bufoff, gbase, voff) do { _Pragma("unroll") for (int _i = 0; _i < 2; ++_i) \
;         __builtin_amdgcn_global_load_lds((const unsigned*)((const char*)(gbase) + (voff)[_i]), (PG8_LAS unsigned*)(lds + (bufoff) + ldsw + _i * 8192), 16, 0, 0); } while (0)
; #define PG8_LDA(dst, b, h) do { _Pragma("unroll") for (int m = 0; m < 4; ++m) _Pragma("unroll") for (int k = 0; k < 2; ++k) dst[m][k] = *(const PG8_LAS bf16x8*)(lds + PG8_SA(b, h) + aoff + m * 2048 + k * 1024); } while (0)
; #define PG8_LDB(dst, b, h) do { _Pragma("unroll") for (int n = 0; n < 2; ++n) _Pragma("unroll") for (int k = 0; k < 2; ++k) dst[n][k] = *(const PG8_LAS bf16x8*)(lds + PG8_SB(b, h) + boff + n * 2048 + k * 1024); } while (0)
; #define PG8_MMA(ai, bj, At, Bt) do { __builtin_amdgcn_s_setprio(1); _Pragma("unroll") for (int m = 0; m < 4; ++m) _Pragma("unroll") for (int n = 0; n < 2; ++n) _Pragma("unroll") for (int k = 0; k < 2; ++k) \
;         acc[ai][bj][m][n] = __builtin_amdgcn_mfma_f32_16x16x32_bf16(Bt[n][k], At[m][k], acc[ai][bj][m][n], 0, 0, 0); __builtin_amdgcn_s_setprio(0); } while (0)
; __device__ __forceinline__ void gemm_phase(PG8_LAS unsigned char* lds, const Gemm g, const StaticOrder& S, const Epi& E, const int tid) {
;     ...
;         for (int t = 0; t < nt; t += 2) {
;             const bool last = (t == nt - 2);
;             const char* a1 = cA + (size_t)(t + 1) * kstep;
;             const char* a2 = last ? nA : cA + (size_t)(t + 2) * kstep; const char* b2 = last ? nB : cB + (size_t)(t + 2) * kstep;
;             const char* a3 = a2 + kstep; const char* b3 = b2 + kstep;
;             PG8_LDB(B0, 0, 0); PG8_LDB(B1, 0, 1); PG8_SCHED; PG8_LDA(At, 0, 0); PG8_STAGE(PG8_SA(1, 1), a1 + hstepA, voffA);
;             PG8_WAIT_V(8); PG8_WAIT_L(0); PG8_BAR; PG8_MMA(0, 0, At, B0); PG8_MMA(0, 1, At, B1); PG8_BAR; PG8_SCHED;
;             PG8_LDA(At, 0, 1); PG8_STAGE(PG8_SB(0, 0), b2, voffB); PG8_STAGE(PG8_SB(0, 1), b2 + hstepB, voffB); PG8_STAGE(PG8_SA(0, 0), a2, voffA);
;             PG8_WAIT_V(8); PG8_WAIT_L(0); PG8_BAR; PG8_MMA(1, 0, At, B0); PG8_MMA(1, 1, At, B1); PG8_BAR; PG8_SCHED;
;     ...
; #pragma unroll
;         for (int a = 0; a < 2; ++a)
; #pragma unroll
;             for (int b = 0; b < 2; ++b)
; #pragma unroll
;                 for (int m = 0; m < 4; ++m)
; #pragma unroll
;                     for (int n = 0; n < 2; ++n) acc[a][b][m][n] = (f32x4){0.f, 0.f, 0.f, 0.f};
.LBB0_87:
	s_add_u32 s10, s10, 0x80
	s_addc_u32 s11, s11, 0
	s_add_u32 s47, s44, 0x100
	s_addc_u32 s48, s45, 0
	s_mov_b32 s44, 0
	s_add_i32 s49, s44, 2
	s_add_u32 s68, s10, 0x80
	s_addc_u32 s45, s11, 0
	s_add_i32 s78, 0, 0x10000
	s_cmp_eq_u32 s15, s44
	s_cselect_b32 s45, s5, s45
	s_cselect_b32 s44, s4, s68
	s_cselect_b32 s69, s39, s48
	s_cselect_b32 s68, s38, s47
	s_add_i32 s79, 0, 0x14000
	v_add_u32_e32 v160, s78, v186
	v_add_u32_e32 v189, s79, v186
	ds_read_b128 v[136:139], v160
	ds_read_b128 v[140:143], v160 offset:1024
	ds_read_b128 v[156:159], v160 offset:2048
	ds_read_b128 v[160:163], v160 offset:3072
	ds_read_b128 v[164:167], v189
	ds_read_b128 v[168:171], v189 offset:1024
	ds_read_b128 v[172:175], v189 offset:2048
	ds_read_b128 v[190:193], v189 offset:3072
	v_lshl_add_u64 v[210:211], s[10:11], 0, v[152:153]
	s_add_i32 m0, s3, 0xc000
	ds_read_b128 v[194:197], v188
	ds_read_b128 v[198:201], v188 offset:1024
	ds_read_b128 v[202:205], v188 offset:2048
	ds_read_b128 v[206:209], v188 offset:3072
	ds_read_b128 v[224:227], v188 offset:4096
	ds_read_b128 v[228:231], v188 offset:5120
	ds_read_b128 v[232:235], v188 offset:6144
	ds_read_b128 v[236:239], v188 offset:7168
	global_load_lds_dwordx4 v[210:211], off
	v_lshl_add_u64 v[210:211], s[10:11], 0, v[154:155]
	s_add_i32 m0, s3, 0xe000
	s_nop 0
	global_load_lds_dwordx4 v[210:211], off
	s_waitcnt vmcnt(8)
	s_waitcnt lgkmcnt(0)
	s_barrier
	s_setprio 1
	s_waitcnt lgkmcnt(0)
	v_mfma_f32_16x16x32_bf16 v[132:135], v[136:139], v[194:197], 0
	v_mfma_f32_16x16x32_bf16 v[128:131], v[156:159], v[194:197], 0
	v_mfma_f32_16x16x32_bf16 v[116:119], v[136:139], v[202:205], 0
	v_mfma_f32_16x16x32_bf16 v[106:109], v[156:159], v[202:205], 0
	v_mfma_f32_16x16x32_bf16 v[94:97], v[136:139], v[224:227], 0
	v_mfma_f32_16x16x32_bf16 v[90:93], v[156:159], v[224:227], 0
	v_mfma_f32_16x16x32_bf16 v[78:81], v[136:139], v[232:235], 0
	v_mfma_f32_16x16x32_bf16 v[74:77], v[156:159], v[232:235], 0
	v_mfma_f32_16x16x32_bf16 v[132:135], v[140:143], v[198:201], v[132:135]
	v_mfma_f32_16x16x32_bf16 v[128:131], v[160:163], v[198:201], v[128:131]
	v_mfma_f32_16x16x32_bf16 v[116:119], v[140:143], v[206:209], v[116:119]
	v_mfma_f32_16x16x32_bf16 v[106:109], v[160:163], v[206:209], v[106:109]
	v_mfma_f32_16x16x32_bf16 v[94:97], v[140:143], v[228:231], v[94:97]
	v_mfma_f32_16x16x32_bf16 v[90:93], v[160:163], v[228:231], v[90:93]
	v_mfma_f32_16x16x32_bf16 v[78:81], v[140:143], v[236:239], v[78:81]
	v_mfma_f32_16x16x32_bf16 v[74:77], v[160:163], v[236:239], v[74:77]
	s_setprio 0
	s_setprio 1
	v_mfma_f32_16x16x32_bf16 v[124:127], v[164:167], v[194:197], 0
	v_mfma_f32_16x16x32_bf16 v[120:123], v[172:175], v[194:197], 0
	v_mfma_f32_16x16x32_bf16 v[102:105], v[164:167], v[202:205], 0
	v_mfma_f32_16x16x32_bf16 v[98:101], v[172:175], v[202:205], 0
	v_mfma_f32_16x16x32_bf16 v[86:89], v[164:167], v[224:227], 0
	v_mfma_f32_16x16x32_bf16 v[82:85], v[172:175], v[224:227], 0
	v_mfma_f32_16x16x32_bf16 v[70:73], v[164:167], v[232:235], 0
	v_mfma_f32_16x16x32_bf16 v[66:69], v[172:175], v[232:235], 0
	v_mfma_f32_16x16x32_bf16 v[124:127], v[168:171], v[198:201], v[124:127]
	v_mfma_f32_16x16x32_bf16 v[120:123], v[190:193], v[198:201], v[120:123]
	v_mfma_f32_16x16x32_bf16 v[102:105], v[168:171], v[206:209], v[102:105]
	v_mfma_f32_16x16x32_bf16 v[98:101], v[190:193], v[206:209], v[98:101]
	v_mfma_f32_16x16x32_bf16 v[86:89], v[168:171], v[228:231], v[86:89]
	v_mfma_f32_16x16x32_bf16 v[82:85], v[190:193], v[228:231], v[82:85]
	v_mfma_f32_16x16x32_bf16 v[70:73], v[168:171], v[236:239], v[70:73]
	v_mfma_f32_16x16x32_bf16 v[66:69], v[190:193], v[236:239], v[66:69]
	s_setprio 0
	s_barrier
	s_add_i32 s78, s78, s31
	v_lshl_add_u64 v[210:211], s[68:69], 0, v[146:147]
	s_mov_b32 m0, s78
	ds_read_b128 v[194:197], v188 offset:16384
	ds_read_b128 v[198:201], v188 offset:17408
	ds_read_b128 v[202:205], v188 offset:18432
	ds_read_b128 v[206:209], v188 offset:19456
	ds_read_b128 v[224:227], v188 offset:20480
	ds_read_b128 v[228:231], v188 offset:21504
	ds_read_b128 v[232:235], v188 offset:22528
	ds_read_b128 v[236:239], v188 offset:23552
	global_load_lds_dwordx4 v[210:211], off
	s_add_i32 m0, s78, 0x2000
	v_lshl_add_u64 v[240:241], s[68:69], 0, v[150:151]
	s_add_u32 s68, s68, s34
	s_addc_u32 s69, s69, 0
	s_add_i32 s78, s79, s31
	global_load_lds_dwordx4 v[240:241], off
	v_lshl_add_u64 v[242:243], s[68:69], 0, v[146:147]
	s_mov_b32 m0, s78
	v_lshl_add_u64 v[244:245], s[68:69], 0, v[150:151]
	global_load_lds_dwordx4 v[242:243], off
	s_add_i32 m0, s78, 0x2000
	v_lshl_add_u64 v[246:247], s[44:45], 0, v[144:145]
	global_load_lds_dwordx4 v[244:245], off
	s_mov_b32 m0, s3
	v_lshl_add_u64 v[248:249], s[44:45], 0, v[148:149]
	global_load_lds_dwordx4 v[246:247], off
	s_mov_b32 m0, s17
	s_nop 0
	global_load_lds_dwordx4 v[248:249], off
	s_waitcnt vmcnt(8)
	s_waitcnt lgkmcnt(0)
	s_barrier
; #define PG8_STAGE(bufoff, gbase, voff) do { _Pragma("unroll") for (int _i = 0; _i < 2; ++_i) \
;         __builtin_amdgcn_global_load_lds((const unsigned*)((const char*)(gbase) + (voff)[_i]), (PG8_LAS unsigned*)(lds + (bufoff) + ldsw + _i * 8192), 16, 0, 0); } while (0)
; #define PG8_LDA(dst, b, h) do { _Pragma("unroll") for (int m = 0; m < 4; ++m) _Pragma("unroll") for (int k = 0; k < 2; ++k) dst[m][k] = *(const PG8_LAS bf16x8*)(lds + PG8_SA(b, h) + aoff + m * 2048 + k * 1024); } while (0)
; #define PG8_LDB(dst, b, h) do { _Pragma("unroll") for (int n = 0; n < 2; ++n) _Pragma("unroll") for (int k = 0; k < 2; ++k) dst[n][k] = *(const PG8_LAS bf16x8*)(lds + PG8_SB(b, h) + boff + n * 2048 + k * 1024); } while (0)
; #define PG8_MMA(ai, bj, At, Bt) do { __builtin_amdgcn_s_setprio(1); _Pragma("unroll") for (int m = 0; m < 4; ++m) _Pragma("unroll") for (int n = 0; n < 2; ++n) _Pragma("unroll") for (int k = 0; k < 2; ++k) \
;         acc[ai][bj][m][n] = __builtin_amdgcn_mfma_f32_16x16x32_bf16(Bt[n][k], At[m][k], acc[ai][bj][m][n], 0, 0, 0); __builtin_amdgcn_s_setprio(0); } while (0)
; #define PG8_WAIT_V(n) asm volatile("s_waitcnt vmcnt(" #n ")" ::: "memory")
; #define PG8_WAIT_L(n) asm volatile("s_waitcnt lgkmcnt(" #n ")" ::: "memory")
; #define PG8_BAR __builtin_amdgcn_s_barrier()
; #define PG8_SCHED __builtin_amdgcn_sched_barrier(0)
; __device__ __forceinline__ void gemm_phase(PG8_LAS unsigned char* lds, const Gemm g, const StaticOrder& S, const Epi& E, const int tid) {
;     ...
;             PG8_WAIT_V(8); PG8_WAIT_L(0); PG8_BAR; PG8_MMA(1, 0, At, B0); PG8_MMA(1, 1, At, B1); PG8_BAR; PG8_SCHED;
;             PG8_LDB(B0, 1, 0); PG8_LDB(B1, 1, 1); PG8_SCHED; PG8_LDA(At, 1, 0); PG8_STAGE(PG8_SA(0, 1), a2 + hstepA, voffA);
;             PG8_WAIT_V(8); PG8_WAIT_L(0); PG8_BAR; PG8_MMA(0, 0, At, B0); PG8_MMA(0, 1, At, B1); PG8_BAR; PG8_SCHED;
	s_setprio 1
	s_waitcnt lgkmcnt(0)
	v_mfma_f32_16x16x32_bf16 v[62:65], v[136:139], v[194:197], 0
	v_mfma_f32_16x16x32_bf16 v[58:61], v[156:159], v[194:197], 0
	v_mfma_f32_16x16x32_bf16 v[46:49], v[136:139], v[202:205], 0
	v_mfma_f32_16x16x32_bf16 v[42:45], v[156:159], v[202:205], 0
	v_mfma_f32_16x16x32_bf16 v[30:33], v[136:139], v[224:227], 0
	v_mfma_f32_16x16x32_bf16 v[26:29], v[156:159], v[224:227], 0
	v_mfma_f32_16x16x32_bf16 v[14:17], v[136:139], v[232:235], 0
	v_mfma_f32_16x16x32_bf16 v[10:13], v[156:159], v[232:235], 0
	v_mfma_f32_16x16x32_bf16 v[62:65], v[140:143], v[198:201], v[62:65]
	v_mfma_f32_16x16x32_bf16 v[58:61], v[160:163], v[198:201], v[58:61]
	v_mfma_f32_16x16x32_bf16 v[46:49], v[140:143], v[206:209], v[46:49]
	v_mfma_f32_16x16x32_bf16 v[42:45], v[160:163], v[206:209], v[42:45]
	v_mfma_f32_16x16x32_bf16 v[30:33], v[140:143], v[228:231], v[30:33]
	v_mfma_f32_16x16x32_bf16 v[26:29], v[160:163], v[228:231], v[26:29]
	v_mfma_f32_16x16x32_bf16 v[14:17], v[140:143], v[236:239], v[14:17]
	v_mfma_f32_16x16x32_bf16 v[10:13], v[160:163], v[236:239], v[10:13]
	s_setprio 0
	s_setprio 1
	v_mfma_f32_16x16x32_bf16 v[54:57], v[164:167], v[194:197], 0
	v_mfma_f32_16x16x32_bf16 v[50:53], v[172:175], v[194:197], 0
	v_mfma_f32_16x16x32_bf16 v[38:41], v[164:167], v[202:205], 0
	v_mfma_f32_16x16x32_bf16 v[34:37], v[172:175], v[202:205], 0
	v_mfma_f32_16x16x32_bf16 v[22:25], v[164:167], v[224:227], 0
	v_mfma_f32_16x16x32_bf16 v[18:21], v[172:175], v[224:227], 0
	v_mfma_f32_16x16x32_bf16 v[6:9], v[164:167], v[232:235], 0
	v_mfma_f32_16x16x32_bf16 v[2:5], v[172:175], v[232:235], 0
	v_mfma_f32_16x16x32_bf16 v[54:57], v[168:171], v[198:201], v[54:57]
	v_mfma_f32_16x16x32_bf16 v[50:53], v[190:193], v[198:201], v[50:53]
	v_mfma_f32_16x16x32_bf16 v[38:41], v[168:171], v[206:209], v[38:41]
	v_mfma_f32_16x16x32_bf16 v[34:37], v[190:193], v[206:209], v[34:37]
	v_mfma_f32_16x16x32_bf16 v[22:25], v[168:171], v[228:231], v[22:25]
	v_mfma_f32_16x16x32_bf16 v[18:21], v[190:193], v[228:231], v[18:21]
	v_mfma_f32_16x16x32_bf16 v[6:9], v[168:171], v[236:239], v[6:9]
	v_mfma_f32_16x16x32_bf16 v[2:5], v[190:193], v[236:239], v[2:5]
	s_setprio 0
	s_barrier
	s_add_i32 s68, 0, 0x18000
	s_add_i32 s69, 0, 0x1c000
	v_add_u32_e32 v160, s68, v186
	v_add_u32_e32 v189, s69, v186
	ds_read_b128 v[136:139], v160
	ds_read_b128 v[140:143], v160 offset:1024
	ds_read_b128 v[156:159], v160 offset:2048
	ds_read_b128 v[160:163], v160 offset:3072
	ds_read_b128 v[164:167], v189
	ds_read_b128 v[168:171], v189 offset:1024
	ds_read_b128 v[172:175], v189 offset:2048
	ds_read_b128 v[190:193], v189 offset:3072
	s_add_u32 s44, s44, s0
	s_addc_u32 s45, s45, 0
	s_mov_b32 m0, s58
	v_lshl_add_u64 v[250:251], s[44:45], 0, v[144:145]
	ds_read_b128 v[194:197], v188 offset:32768
	ds_read_b128 v[198:201], v188 offset:33792
	ds_read_b128 v[202:205], v188 offset:34816
	ds_read_b128 v[206:209], v188 offset:35840
	ds_read_b128 v[224:227], v188 offset:36864
	ds_read_b128 v[228:231], v188 offset:37888
	ds_read_b128 v[232:235], v188 offset:38912
	ds_read_b128 v[236:239], v188 offset:39936
	global_load_lds_dwordx4 v[250:251], off
	v_lshl_add_u64 v[250:251], s[44:45], 0, v[148:149]
	s_mov_b32 m0, s59
	s_nop 0
	global_load_lds_dwordx4 v[250:251], off
	s_waitcnt vmcnt(8)
	s_waitcnt lgkmcnt(0)
	s_barrier
	s_setprio 1
	s_waitcnt lgkmcnt(0)
	v_mfma_f32_16x16x32_bf16 v[132:135], v[136:139], v[194:197], v[132:135]
	v_mfma_f32_16x16x32_bf16 v[128:131], v[156:159], v[194:197], v[128:131]
	v_mfma_f32_16x16x32_bf16 v[116:119], v[136:139], v[202:205], v[116:119]
	v_mfma_f32_16x16x32_bf16 v[106:109], v[156:159], v[202:205], v[106:109]
	v_mfma_f32_16x16x32_bf16 v[94:97], v[136:139], v[224:227], v[94:97]
	v_mfma_f32_16x16x32_bf16 v[90:93], v[156:159], v[224:227], v[90:93]
	v_mfma_f32_16x16x32_bf16 v[78:81], v[136:139], v[232:235], v[78:81]
	v_mfma_f32_16x16x32_bf16 v[74:77], v[156:159], v[232:235], v[74:77]
	v_mfma_f32_16x16x32_bf16 v[132:135], v[140:143], v[198:201], v[132:135]
	v_mfma_f32_16x16x32_bf16 v[128:131], v[160:163], v[198:201], v[128:131]
	v_mfma_f32_16x16x32_bf16 v[116:119], v[140:143], v[206:209], v[116:119]
	v_mfma_f32_16x16x32_bf16 v[106:109], v[160:163], v[206:209], v[106:109]
	v_mfma_f32_16x16x32_bf16 v[94:97], v[140:143], v[228:231], v[94:97]
	v_mfma_f32_16x16x32_bf16 v[90:93], v[160:163], v[228:231], v[90:93]
	v_mfma_f32_16x16x32_bf16 v[78:81], v[140:143], v[236:239], v[78:81]
	v_mfma_f32_16x16x32_bf16 v[74:77], v[160:163], v[236:239], v[74:77]
	s_setprio 0
	s_setprio 1
	v_mfma_f32_16x16x32_bf16 v[124:127], v[164:167], v[194:197], v[124:127]
	v_mfma_f32_16x16x32_bf16 v[120:123], v[172:175], v[194:197], v[120:123]
	v_mfma_f32_16x16x32_bf16 v[102:105], v[164:167], v[202:205], v[102:105]
	v_mfma_f32_16x16x32_bf16 v[98:101], v[172:175], v[202:205], v[98:101]
	v_mfma_f32_16x16x32_bf16 v[86:89], v[164:167], v[224:227], v[86:89]
	v_mfma_f32_16x16x32_bf16 v[82:85], v[172:175], v[224:227], v[82:85]
	v_mfma_f32_16x16x32_bf16 v[70:73], v[164:167], v[232:235], v[70:73]
	v_mfma_f32_16x16x32_bf16 v[66:69], v[172:175], v[232:235], v[66:69]
	v_mfma_f32_16x16x32_bf16 v[124:127], v[168:171], v[198:201], v[124:127]
	v_mfma_f32_16x16x32_bf16 v[120:123], v[190:193], v[198:201], v[120:123]
	v_mfma_f32_16x16x32_bf16 v[102:105], v[168:171], v[206:209], v[102:105]
	v_mfma_f32_16x16x32_bf16 v[98:101], v[190:193], v[206:209], v[98:101]
	v_mfma_f32_16x16x32_bf16 v[86:89], v[168:171], v[228:231], v[86:89]
	v_mfma_f32_16x16x32_bf16 v[82:85], v[190:193], v[228:231], v[82:85]
	v_mfma_f32_16x16x32_bf16 v[70:73], v[168:171], v[236:239], v[70:73]
	v_mfma_f32_16x16x32_bf16 v[66:69], v[190:193], v[236:239], v[66:69]
	s_setprio 0
	s_barrier
; #define PG8_STAGE(bufoff, gbase, voff) do { _Pragma("unroll") for (int _i = 0; _i < 2; ++_i) \
;         __builtin_amdgcn_global_load_lds((const unsigned*)((const char*)(gbase) + (voff)[_i]), (PG8_LAS unsigned*)(lds + (bufoff) + ldsw + _i * 8192), 16, 0, 0); } while (0)
; #define PG8_LDA(dst, b, h) do { _Pragma("unroll") for (int m = 0; m < 4; ++m) _Pragma("unroll") for (int k = 0; k < 2; ++k) dst[m][k] = *(const PG8_LAS bf16x8*)(lds + PG8_SA(b, h) + aoff + m * 2048 + k * 1024); } while (0)
; #define PG8_LDB(dst, b, h) do { _Pragma("unroll") for (int n = 0; n < 2; ++n) _Pragma("unroll") for (int k = 0; k < 2; ++k) dst[n][k] = *(const PG8_LAS bf16x8*)(lds + PG8_SB(b, h) + boff + n * 2048 + k * 1024); } while (0)
; #define PG8_MMA(ai, bj, At, Bt) do { __builtin_amdgcn_s_setprio(1); _Pragma("unroll") for (int m = 0; m < 4; ++m) _Pragma("unroll") for (int n = 0; n < 2; ++n) _Pragma("unroll") for (int k = 0; k < 2; ++k) \
;         acc[ai][bj][m][n] = __builtin_amdgcn_mfma_f32_16x16x32_bf16(Bt[n][k], At[m][k], acc[ai][bj][m][n], 0, 0, 0); __builtin_amdgcn_s_setprio(0); } while (0)
; #define PG8_WAIT_V(n) asm volatile("s_waitcnt vmcnt(" #n ")" ::: "memory")
; #define PG8_WAIT_L(n) asm volatile("s_waitcnt lgkmcnt(" #n ")" ::: "memory")
; #define PG8_BAR __builtin_amdgcn_s_barrier()
; #define PG8_SCHED __builtin_amdgcn_sched_barrier(0)
; __device__ __forceinline__ void gemm_phase(PG8_LAS unsigned char* lds, const Gemm g, const StaticOrder& S, const Epi& E, const int tid) {
;     ...
;         for (int t = 0; t < nt; t += 2) {
;             const bool last = (t == nt - 2);
;             const char* a1 = cA + (size_t)(t + 1) * kstep;
;             const char* a2 = last ? nA : cA + (size_t)(t + 2) * kstep; const char* b2 = last ? nB : cB + (size_t)(t + 2) * kstep;
;             const char* a3 = a2 + kstep; const char* b3 = b2 + kstep;
;             PG8_LDB(B0, 0, 0); PG8_LDB(B1, 0, 1); PG8_SCHED; PG8_LDA(At, 0, 0); PG8_STAGE(PG8_SA(1, 1), a1 + hstepA, voffA);
;             PG8_WAIT_V(8); PG8_WAIT_L(0); PG8_BAR; PG8_MMA(0, 0, At, B0); PG8_MMA(0, 1, At, B1); PG8_BAR; PG8_SCHED;
;     ...
;             PG8_LDA(At, 1, 1); PG8_STAGE(PG8_SB(1, 0), b3, voffB); PG8_STAGE(PG8_SB(1, 1), b3 + hstepB, voffB); PG8_STAGE(PG8_SA(1, 0), a3, voffA);
;             PG8_WAIT_V(8); PG8_WAIT_L(0); PG8_BAR; PG8_MMA(1, 0, At, B0); PG8_MMA(1, 1, At, B1); PG8_BAR; PG8_SCHED;
;         }
	s_add_i32 s44, s68, s31
	v_lshl_add_u64 v[210:211], v[210:211], 0, s[36:37]
	s_mov_b32 m0, s44
	ds_read_b128 v[194:197], v188 offset:49152
	ds_read_b128 v[198:201], v188 offset:50176
	ds_read_b128 v[202:205], v188 offset:51200
	ds_read_b128 v[206:209], v188 offset:52224
	ds_read_b128 v[224:227], v188 offset:53248
	ds_read_b128 v[228:231], v188 offset:54272
	ds_read_b128 v[232:235], v188 offset:55296
	ds_read_b128 v[236:239], v188 offset:56320
	global_load_lds_dwordx4 v[210:211], off
	v_lshl_add_u64 v[210:211], v[240:241], 0, s[36:37]
	s_add_i32 m0, s44, 0x2000
	s_add_i32 s44, s69, s31
	global_load_lds_dwordx4 v[210:211], off
	v_lshl_add_u64 v[210:211], v[242:243], 0, s[36:37]
	s_mov_b32 m0, s44
	s_nop 0
	global_load_lds_dwordx4 v[210:211], off
	v_lshl_add_u64 v[210:211], v[244:245], 0, s[36:37]
	s_add_i32 m0, s44, 0x2000
	s_nop 0
	global_load_lds_dwordx4 v[210:211], off
	v_lshl_add_u64 v[210:211], v[246:247], 0, s[36:37]
	s_mov_b32 m0, s12
	s_nop 0
	global_load_lds_dwordx4 v[210:211], off
	v_lshl_add_u64 v[210:211], v[248:249], 0, s[36:37]
	s_mov_b32 m0, s13
	s_nop 0
	global_load_lds_dwordx4 v[210:211], off
	s_waitcnt vmcnt(8)
	s_waitcnt lgkmcnt(0)
	s_barrier
	s_setprio 1
	s_waitcnt lgkmcnt(0)
	v_mfma_f32_16x16x32_bf16 v[62:65], v[136:139], v[194:197], v[62:65]
	v_mfma_f32_16x16x32_bf16 v[58:61], v[156:159], v[194:197], v[58:61]
	v_mfma_f32_16x16x32_bf16 v[46:49], v[136:139], v[202:205], v[46:49]
	v_mfma_f32_16x16x32_bf16 v[42:45], v[156:159], v[202:205], v[42:45]
	v_mfma_f32_16x16x32_bf16 v[30:33], v[136:139], v[224:227], v[30:33]
	v_mfma_f32_16x16x32_bf16 v[26:29], v[156:159], v[224:227], v[26:29]
	v_mfma_f32_16x16x32_bf16 v[14:17], v[136:139], v[232:235], v[14:17]
	v_mfma_f32_16x16x32_bf16 v[10:13], v[156:159], v[232:235], v[10:13]
	v_mfma_f32_16x16x32_bf16 v[62:65], v[140:143], v[198:201], v[62:65]
	v_mfma_f32_16x16x32_bf16 v[58:61], v[160:163], v[198:201], v[58:61]
	v_mfma_f32_16x16x32_bf16 v[46:49], v[140:143], v[206:209], v[46:49]
	v_mfma_f32_16x16x32_bf16 v[42:45], v[160:163], v[206:209], v[42:45]
	v_mfma_f32_16x16x32_bf16 v[30:33], v[140:143], v[228:231], v[30:33]
	v_mfma_f32_16x16x32_bf16 v[26:29], v[160:163], v[228:231], v[26:29]
	v_mfma_f32_16x16x32_bf16 v[14:17], v[140:143], v[236:239], v[14:17]
	v_mfma_f32_16x16x32_bf16 v[10:13], v[160:163], v[236:239], v[10:13]
	s_setprio 0
	s_setprio 1
	v_mfma_f32_16x16x32_bf16 v[54:57], v[164:167], v[194:197], v[54:57]
	v_mfma_f32_16x16x32_bf16 v[50:53], v[172:175], v[194:197], v[50:53]
	v_mfma_f32_16x16x32_bf16 v[38:41], v[164:167], v[202:205], v[38:41]
	v_mfma_f32_16x16x32_bf16 v[34:37], v[172:175], v[202:205], v[34:37]
	v_mfma_f32_16x16x32_bf16 v[22:25], v[164:167], v[224:227], v[22:25]
	v_mfma_f32_16x16x32_bf16 v[18:21], v[172:175], v[224:227], v[18:21]
	v_mfma_f32_16x16x32_bf16 v[6:9], v[164:167], v[232:235], v[6:9]
	v_mfma_f32_16x16x32_bf16 v[2:5], v[172:175], v[232:235], v[2:5]
	v_mfma_f32_16x16x32_bf16 v[54:57], v[168:171], v[198:201], v[54:57]
	v_mfma_f32_16x16x32_bf16 v[50:53], v[190:193], v[198:201], v[50:53]
	v_mfma_f32_16x16x32_bf16 v[38:41], v[168:171], v[206:209], v[38:41]
	v_mfma_f32_16x16x32_bf16 v[34:37], v[190:193], v[206:209], v[34:37]
	v_mfma_f32_16x16x32_bf16 v[22:25], v[168:171], v[228:231], v[22:25]
	v_mfma_f32_16x16x32_bf16 v[18:21], v[190:193], v[228:231], v[18:21]
	v_mfma_f32_16x16x32_bf16 v[6:9], v[168:171], v[236:239], v[6:9]
	v_mfma_f32_16x16x32_bf16 v[2:5], v[190:193], v[236:239], v[2:5]
	s_setprio 0
	s_barrier
	s_add_u32 s10, s10, 0x100
	s_addc_u32 s11, s11, 0
	s_add_u32 s47, s47, 0x100
	s_addc_u32 s48, s48, 0
	s_cmp_ge_u32 s49, s14
	s_mov_b32 s44, s49
	s_cbranch_scc1 .Lk_peel_done
	.p2align 6
.LBB0_88:
	s_add_i32 s49, s44, 2
	s_add_u32 s68, s10, 0x80
	s_addc_u32 s45, s11, 0
	s_add_i32 s78, 0, 0x10000
	s_cmp_eq_u32 s15, s44
	s_cselect_b32 s45, s5, s45
	s_cselect_b32 s44, s4, s68
	s_cselect_b32 s69, s39, s48
	s_cselect_b32 s68, s38, s47
	s_add_i32 s79, 0, 0x14000
	v_add_u32_e32 v160, s78, v186
	v_add_u32_e32 v189, s79, v186
	ds_read_b128 v[136:139], v160
	ds_read_b128 v[140:143], v160 offset:1024
	ds_read_b128 v[156:159], v160 offset:2048
	ds_read_b128 v[160:163], v160 offset:3072
	ds_read_b128 v[164:167], v189
	ds_read_b128 v[168:171], v189 offset:1024
	ds_read_b128 v[172:175], v189 offset:2048
	ds_read_b128 v[190:193], v189 offset:3072
	v_lshl_add_u64 v[210:211], s[10:11], 0, v[152:153]
	s_add_i32 m0, s3, 0xc000
	ds_read_b128 v[194:197], v188
	ds_read_b128 v[198:201], v188 offset:1024
	ds_read_b128 v[202:205], v188 offset:2048
	ds_read_b128 v[206:209], v188 offset:3072
	ds_read_b128 v[224:227], v188 offset:4096
	ds_read_b128 v[228:231], v188 offset:5120
	ds_read_b128 v[232:235], v188 offset:6144
	ds_read_b128 v[236:239], v188 offset:7168
	global_load_lds_dwordx4 v[210:211], off
	v_lshl_add_u64 v[210:211], s[10:11], 0, v[154:155]
	s_add_i32 m0, s3, 0xe000
	s_nop 0
	global_load_lds_dwordx4 v[210:211], off
	s_waitcnt vmcnt(8)
	s_waitcnt lgkmcnt(0)
	s_barrier
; #define PG8_STAGE(bufoff, gbase, voff) do { _Pragma("unroll") for (int _i = 0; _i < 2; ++_i) \
;         __builtin_amdgcn_global_load_lds((const unsigned*)((const char*)(gbase) + (voff)[_i]), (PG8_LAS unsigned*)(lds + (bufoff) + ldsw + _i * 8192), 16, 0, 0); } while (0)
; #define PG8_LDA(dst, b, h) do { _Pragma("unroll") for (int m = 0; m < 4; ++m) _Pragma("unroll") for (int k = 0; k < 2; ++k) dst[m][k] = *(const PG8_LAS bf16x8*)(lds + PG8_SA(b, h) + aoff + m * 2048 + k * 1024); } while (0)
; #define PG8_LDB(dst, b, h) do { _Pragma("unroll") for (int n = 0; n < 2; ++n) _Pragma("unroll") for (int k = 0; k < 2; ++k) dst[n][k] = *(const PG8_LAS bf16x8*)(lds + PG8_SB(b, h) + boff + n * 2048 + k * 1024); } while (0)
; #define PG8_MMA(ai, bj, At, Bt) do { __builtin_amdgcn_s_setprio(1); _Pragma("unroll") for (int m = 0; m < 4; ++m) _Pragma("unroll") for (int n = 0; n < 2; ++n) _Pragma("unroll") for (int k = 0; k < 2; ++k) \
;         acc[ai][bj][m][n] = __builtin_amdgcn_mfma_f32_16x16x32_bf16(Bt[n][k], At[m][k], acc[ai][bj][m][n], 0, 0, 0); __builtin_amdgcn_s_setprio(0); } while (0)
; #define PG8_WAIT_V(n) asm volatile("s_waitcnt vmcnt(" #n ")" ::: "memory")
; #define PG8_WAIT_L(n) asm volatile("s_waitcnt lgkmcnt(" #n ")" ::: "memory")
; #define PG8_BAR __builtin_amdgcn_s_barrier()
; #define PG8_SCHED __builtin_amdgcn_sched_barrier(0)
; __device__ __forceinline__ void gemm_phase(PG8_LAS unsigned char* lds, const Gemm g, const StaticOrder& S, const Epi& E, const int tid) {
;     ...
;             PG8_WAIT_V(8); PG8_WAIT_L(0); PG8_BAR; PG8_MMA(0, 0, At, B0); PG8_MMA(0, 1, At, B1); PG8_BAR; PG8_SCHED;
;             PG8_LDA(At, 0, 1); PG8_STAGE(PG8_SB(0, 0), b2, voffB); PG8_STAGE(PG8_SB(0, 1), b2 + hstepB, voffB); PG8_STAGE(PG8_SA(0, 0), a2, voffA);
;             PG8_WAIT_V(8); PG8_WAIT_L(0); PG8_BAR; PG8_MMA(1, 0, At, B0); PG8_MMA(1, 1, At, B1); PG8_BAR; PG8_SCHED;
;             PG8_LDB(B0, 1, 0); PG8_LDB(B1, 1, 1); PG8_SCHED; PG8_LDA(At, 1, 0); PG8_STAGE(PG8_SA(0, 1), a2 + hstepA, voffA);
;             PG8_WAIT_V(8); PG8_WAIT_L(0); PG8_BAR; PG8_MMA(0, 0, At, B0); PG8_MMA(0, 1, At, B1); PG8_BAR; PG8_SCHED;
	s_setprio 1
	s_waitcnt lgkmcnt(0)
	v_mfma_f32_16x16x32_bf16 v[132:135], v[136:139], v[194:197], v[132:135]
	v_mfma_f32_16x16x32_bf16 v[128:131], v[156:159], v[194:197], v[128:131]
	v_mfma_f32_16x16x32_bf16 v[116:119], v[136:139], v[202:205], v[116:119]
	v_mfma_f32_16x16x32_bf16 v[106:109], v[156:159], v[202:205], v[106:109]
	v_mfma_f32_16x16x32_bf16 v[94:97], v[136:139], v[224:227], v[94:97]
	v_mfma_f32_16x16x32_bf16 v[90:93], v[156:159], v[224:227], v[90:93]
	v_mfma_f32_16x16x32_bf16 v[78:81], v[136:139], v[232:235], v[78:81]
	v_mfma_f32_16x16x32_bf16 v[74:77], v[156:159], v[232:235], v[74:77]
	v_mfma_f32_16x16x32_bf16 v[132:135], v[140:143], v[198:201], v[132:135]
	v_mfma_f32_16x16x32_bf16 v[128:131], v[160:163], v[198:201], v[128:131]
	v_mfma_f32_16x16x32_bf16 v[116:119], v[140:143], v[206:209], v[116:119]
	v_mfma_f32_16x16x32_bf16 v[106:109], v[160:163], v[206:209], v[106:109]
	v_mfma_f32_16x16x32_bf16 v[94:97], v[140:143], v[228:231], v[94:97]
	v_mfma_f32_16x16x32_bf16 v[90:93], v[160:163], v[228:231], v[90:93]
	v_mfma_f32_16x16x32_bf16 v[78:81], v[140:143], v[236:239], v[78:81]
	v_mfma_f32_16x16x32_bf16 v[74:77], v[160:163], v[236:239], v[74:77]
	s_setprio 0
	s_setprio 1
	v_mfma_f32_16x16x32_bf16 v[124:127], v[164:167], v[194:197], v[124:127]
	v_mfma_f32_16x16x32_bf16 v[120:123], v[172:175], v[194:197], v[120:123]
	v_mfma_f32_16x16x32_bf16 v[102:105], v[164:167], v[202:205], v[102:105]
	v_mfma_f32_16x16x32_bf16 v[98:101], v[172:175], v[202:205], v[98:101]
	v_mfma_f32_16x16x32_bf16 v[86:89], v[164:167], v[224:227], v[86:89]
	v_mfma_f32_16x16x32_bf16 v[82:85], v[172:175], v[224:227], v[82:85]
	v_mfma_f32_16x16x32_bf16 v[70:73], v[164:167], v[232:235], v[70:73]
	v_mfma_f32_16x16x32_bf16 v[66:69], v[172:175], v[232:235], v[66:69]
	v_mfma_f32_16x16x32_bf16 v[124:127], v[168:171], v[198:201], v[124:127]
	v_mfma_f32_16x16x32_bf16 v[120:123], v[190:193], v[198:201], v[120:123]
	v_mfma_f32_16x16x32_bf16 v[102:105], v[168:171], v[206:209], v[102:105]
	v_mfma_f32_16x16x32_bf16 v[98:101], v[190:193], v[206:209], v[98:101]
	v_mfma_f32_16x16x32_bf16 v[86:89], v[168:171], v[228:231], v[86:89]
	v_mfma_f32_16x16x32_bf16 v[82:85], v[190:193], v[228:231], v[82:85]
	v_mfma_f32_16x16x32_bf16 v[70:73], v[168:171], v[236:239], v[70:73]
	v_mfma_f32_16x16x32_bf16 v[66:69], v[190:193], v[236:239], v[66:69]
	s_setprio 0
	s_barrier
	s_add_i32 s78, s78, s31
	v_lshl_add_u64 v[210:211], s[68:69], 0, v[146:147]
	s_mov_b32 m0, s78
	ds_read_b128 v[194:197], v188 offset:16384
	ds_read_b128 v[198:201], v188 offset:17408
	ds_read_b128 v[202:205], v188 offset:18432
	ds_read_b128 v[206:209], v188 offset:19456
	ds_read_b128 v[224:227], v188 offset:20480
	ds_read_b128 v[228:231], v188 offset:21504
	ds_read_b128 v[232:235], v188 offset:22528
	ds_read_b128 v[236:239], v188 offset:23552
	global_load_lds_dwordx4 v[210:211], off
	s_add_i32 m0, s78, 0x2000
	v_lshl_add_u64 v[240:241], s[68:69], 0, v[150:151]
	s_add_u32 s68, s68, s34
	s_addc_u32 s69, s69, 0
	s_add_i32 s78, s79, s31
	global_load_lds_dwordx4 v[240:241], off
	v_lshl_add_u64 v[242:243], s[68:69], 0, v[146:147]
	s_mov_b32 m0, s78
	v_lshl_add_u64 v[244:245], s[68:69], 0, v[150:151]
	global_load_lds_dwordx4 v[242:243], off
	s_add_i32 m0, s78, 0x2000
	v_lshl_add_u64 v[246:247], s[44:45], 0, v[144:145]
	global_load_lds_dwordx4 v[244:245], off
	s_mov_b32 m0, s3
	v_lshl_add_u64 v[248:249], s[44:45], 0, v[148:149]
	global_load_lds_dwordx4 v[246:247], off
	s_mov_b32 m0, s17
	s_nop 0
	global_load_lds_dwordx4 v[248:249], off
	s_waitcnt vmcnt(8)
	s_waitcnt lgkmcnt(0)
	s_barrier
	s_setprio 1
	s_waitcnt lgkmcnt(0)
	v_mfma_f32_16x16x32_bf16 v[62:65], v[136:139], v[194:197], v[62:65]
	v_mfma_f32_16x16x32_bf16 v[58:61], v[156:159], v[194:197], v[58:61]
	v_mfma_f32_16x16x32_bf16 v[46:49], v[136:139], v[202:205], v[46:49]
	v_mfma_f32_16x16x32_bf16 v[42:45], v[156:159], v[202:205], v[42:45]
	v_mfma_f32_16x16x32_bf16 v[30:33], v[136:139], v[224:227], v[30:33]
	v_mfma_f32_16x16x32_bf16 v[26:29], v[156:159], v[224:227], v[26:29]
	v_mfma_f32_16x16x32_bf16 v[14:17], v[136:139], v[232:235], v[14:17]
	v_mfma_f32_16x16x32_bf16 v[10:13], v[156:159], v[232:235], v[10:13]
	v_mfma_f32_16x16x32_bf16 v[62:65], v[140:143], v[198:201], v[62:65]
	v_mfma_f32_16x16x32_bf16 v[58:61], v[160:163], v[198:201], v[58:61]
	v_mfma_f32_16x16x32_bf16 v[46:49], v[140:143], v[206:209], v[46:49]
	v_mfma_f32_16x16x32_bf16 v[42:45], v[160:163], v[206:209], v[42:45]
	v_mfma_f32_16x16x32_bf16 v[30:33], v[140:143], v[228:231], v[30:33]
	v_mfma_f32_16x16x32_bf16 v[26:29], v[160:163], v[228:231], v[26:29]
	v_mfma_f32_16x16x32_bf16 v[14:17], v[140:143], v[236:239], v[14:17]
	v_mfma_f32_16x16x32_bf16 v[10:13], v[160:163], v[236:239], v[10:13]
	s_setprio 0
	s_setprio 1
	v_mfma_f32_16x16x32_bf16 v[54:57], v[164:167], v[194:197], v[54:57]
	v_mfma_f32_16x16x32_bf16 v[50:53], v[172:175], v[194:197], v[50:53]
	v_mfma_f32_16x16x32_bf16 v[38:41], v[164:167], v[202:205], v[38:41]
	v_mfma_f32_16x16x32_bf16 v[34:37], v[172:175], v[202:205], v[34:37]
	v_mfma_f32_16x16x32_bf16 v[22:25], v[164:167], v[224:227], v[22:25]
	v_mfma_f32_16x16x32_bf16 v[18:21], v[172:175], v[224:227], v[18:21]
	v_mfma_f32_16x16x32_bf16 v[6:9], v[164:167], v[232:235], v[6:9]
	v_mfma_f32_16x16x32_bf16 v[2:5], v[172:175], v[232:235], v[2:5]
	v_mfma_f32_16x16x32_bf16 v[54:57], v[168:171], v[198:201], v[54:57]
	v_mfma_f32_16x16x32_bf16 v[50:53], v[190:193], v[198:201], v[50:53]
	v_mfma_f32_16x16x32_bf16 v[38:41], v[168:171], v[206:209], v[38:41]
	v_mfma_f32_16x16x32_bf16 v[34:37], v[190:193], v[206:209], v[34:37]
	v_mfma_f32_16x16x32_bf16 v[22:25], v[168:171], v[228:231], v[22:25]
	v_mfma_f32_16x16x32_bf16 v[18:21], v[190:193], v[228:231], v[18:21]
	v_mfma_f32_16x16x32_bf16 v[6:9], v[168:171], v[236:239], v[6:9]
	v_mfma_f32_16x16x32_bf16 v[2:5], v[190:193], v[236:239], v[2:5]
	s_setprio 0
	s_barrier
; #define PG8_STAGE(bufoff, gbase, voff) do { _Pragma("unroll") for (int _i = 0; _i < 2; ++_i) \
;         __builtin_amdgcn_global_load_lds((const unsigned*)((const char*)(gbase) + (voff)[_i]), (PG8_LAS unsigned*)(lds + (bufoff) + ldsw + _i * 8192), 16, 0, 0); } while (0)
; #define PG8_LDA(dst, b, h) do { _Pragma("unroll") for (int m = 0; m < 4; ++m) _Pragma("unroll") for (int k = 0; k < 2; ++k) dst[m][k] = *(const PG8_LAS bf16x8*)(lds + PG8_SA(b, h) + aoff + m * 2048 + k * 1024); } while (0)
; #define PG8_LDB(dst, b, h) do { _Pragma("unroll") for (int n = 0; n < 2; ++n) _Pragma("unroll") for (int k = 0; k < 2; ++k) dst[n][k] = *(const PG8_LAS bf16x8*)(lds + PG8_SB(b, h) + boff + n * 2048 + k * 1024); } while (0)
; #define PG8_MMA(ai, bj, At, Bt) do { __builtin_amdgcn_s_setprio(1); _Pragma("unroll") for (int m = 0; m < 4; ++m) _Pragma("unroll") for (int n = 0; n < 2; ++n) _Pragma("unroll") for (int k = 0; k < 2; ++k) \
;         acc[ai][bj][m][n] = __builtin_amdgcn_mfma_f32_16x16x32_bf16(Bt[n][k], At[m][k], acc[ai][bj][m][n], 0, 0, 0); __builtin_amdgcn_s_setprio(0); } while (0)
; #define PG8_WAIT_V(n) asm volatile("s_waitcnt vmcnt(" #n ")" ::: "memory")
; #define PG8_WAIT_L(n) asm volatile("s_waitcnt lgkmcnt(" #n ")" ::: "memory")
; #define PG8_BAR __builtin_amdgcn_s_barrier()
; #define PG8_SCHED __builtin_amdgcn_sched_barrier(0)
; __device__ __forceinline__ void gemm_phase(PG8_LAS unsigned char* lds, const Gemm g, const StaticOrder& S, const Epi& E, const int tid) {
;     ...
;             PG8_LDB(B0, 1, 0); PG8_LDB(B1, 1, 1); PG8_SCHED; PG8_LDA(At, 1, 0); PG8_STAGE(PG8_SA(0, 1), a2 + hstepA, voffA);
;             PG8_WAIT_V(8); PG8_WAIT_L(0); PG8_BAR; PG8_MMA(0, 0, At, B0); PG8_MMA(0, 1, At, B1); PG8_BAR; PG8_SCHED;
	s_add_i32 s68, 0, 0x18000
	s_add_i32 s69, 0, 0x1c000
	v_add_u32_e32 v160, s68, v186
	v_add_u32_e32 v189, s69, v186
	ds_read_b128 v[136:139], v160
	ds_read_b128 v[140:143], v160 offset:1024
	ds_read_b128 v[156:159], v160 offset:2048
	ds_read_b128 v[160:163], v160 offset:3072
	ds_read_b128 v[164:167], v189
	ds_read_b128 v[168:171], v189 offset:1024
	ds_read_b128 v[172:175], v189 offset:2048
	ds_read_b128 v[190:193], v189 offset:3072
	s_add_u32 s44, s44, s0
	s_addc_u32 s45, s45, 0
	s_mov_b32 m0, s58
	v_lshl_add_u64 v[250:251], s[44:45], 0, v[144:145]
	ds_read_b128 v[194:197], v188 offset:32768
	ds_read_b128 v[198:201], v188 offset:33792
	ds_read_b128 v[202:205], v188 offset:34816
	ds_read_b128 v[206:209], v188 offset:35840
	ds_read_b128 v[224:227], v188 offset:36864
	ds_read_b128 v[228:231], v188 offset:37888
	ds_read_b128 v[232:235], v188 offset:38912
	ds_read_b128 v[236:239], v188 offset:39936
	global_load_lds_dwordx4 v[250:251], off
	v_lshl_add_u64 v[250:251], s[44:45], 0, v[148:149]
	s_mov_b32 m0, s59
	s_nop 0
	global_load_lds_dwordx4 v[250:251], off
	s_waitcnt vmcnt(8)
	s_waitcnt lgkmcnt(0)
	s_barrier
	s_setprio 1
	s_waitcnt lgkmcnt(0)
	v_mfma_f32_16x16x32_bf16 v[132:135], v[136:139], v[194:197], v[132:135]
	v_mfma_f32_16x16x32_bf16 v[128:131], v[156:159], v[194:197], v[128:131]
	v_mfma_f32_16x16x32_bf16 v[116:119], v[136:139], v[202:205], v[116:119]
	v_mfma_f32_16x16x32_bf16 v[106:109], v[156:159], v[202:205], v[106:109]
	v_mfma_f32_16x16x32_bf16 v[94:97], v[136:139], v[224:227], v[94:97]
	v_mfma_f32_16x16x32_bf16 v[90:93], v[156:159], v[224:227], v[90:93]
	v_mfma_f32_16x16x32_bf16 v[78:81], v[136:139], v[232:235], v[78:81]
	v_mfma_f32_16x16x32_bf16 v[74:77], v[156:159], v[232:235], v[74:77]
	v_mfma_f32_16x16x32_bf16 v[132:135], v[140:143], v[198:201], v[132:135]
	v_mfma_f32_16x16x32_bf16 v[128:131], v[160:163], v[198:201], v[128:131]
	v_mfma_f32_16x16x32_bf16 v[116:119], v[140:143], v[206:209], v[116:119]
	v_mfma_f32_16x16x32_bf16 v[106:109], v[160:163], v[206:209], v[106:109]
	v_mfma_f32_16x16x32_bf16 v[94:97], v[140:143], v[228:231], v[94:97]
	v_mfma_f32_16x16x32_bf16 v[90:93], v[160:163], v[228:231], v[90:93]
	v_mfma_f32_16x16x32_bf16 v[78:81], v[140:143], v[236:239], v[78:81]
	v_mfma_f32_16x16x32_bf16 v[74:77], v[160:163], v[236:239], v[74:77]
	s_setprio 0
	s_setprio 1
	v_mfma_f32_16x16x32_bf16 v[124:127], v[164:167], v[194:197], v[124:127]
	v_mfma_f32_16x16x32_bf16 v[120:123], v[172:175], v[194:197], v[120:123]
	v_mfma_f32_16x16x32_bf16 v[102:105], v[164:167], v[202:205], v[102:105]
	v_mfma_f32_16x16x32_bf16 v[98:101], v[172:175], v[202:205], v[98:101]
	v_mfma_f32_16x16x32_bf16 v[86:89], v[164:167], v[224:227], v[86:89]
	v_mfma_f32_16x16x32_bf16 v[82:85], v[172:175], v[224:227], v[82:85]
	v_mfma_f32_16x16x32_bf16 v[70:73], v[164:167], v[232:235], v[70:73]
	v_mfma_f32_16x16x32_bf16 v[66:69], v[172:175], v[232:235], v[66:69]
	v_mfma_f32_16x16x32_bf16 v[124:127], v[168:171], v[198:201], v[124:127]
	v_mfma_f32_16x16x32_bf16 v[120:123], v[190:193], v[198:201], v[120:123]
	v_mfma_f32_16x16x32_bf16 v[102:105], v[168:171], v[206:209], v[102:105]
	v_mfma_f32_16x16x32_bf16 v[98:101], v[190:193], v[206:209], v[98:101]
	v_mfma_f32_16x16x32_bf16 v[86:89], v[168:171], v[228:231], v[86:89]
	v_mfma_f32_16x16x32_bf16 v[82:85], v[190:193], v[228:231], v[82:85]
	v_mfma_f32_16x16x32_bf16 v[70:73], v[168:171], v[236:239], v[70:73]
	v_mfma_f32_16x16x32_bf16 v[66:69], v[190:193], v[236:239], v[66:69]
	s_setprio 0
	s_barrier
; #define PG8_STAGE(bufoff, gbase, voff) do { _Pragma("unroll") for (int _i = 0; _i < 2; ++_i) \
;         __builtin_amdgcn_global_load_lds((const unsigned*)((const char*)(gbase) + (voff)[_i]), (PG8_LAS unsigned*)(lds + (bufoff) + ldsw + _i * 8192), 16, 0, 0); } while (0)
; #define PG8_LDA(dst, b, h) do { _Pragma("unroll") for (int m = 0; m < 4; ++m) _Pragma("unroll") for (int k = 0; k < 2; ++k) dst[m][k] = *(const PG8_LAS bf16x8*)(lds + PG8_SA(b, h) + aoff + m * 2048 + k * 1024); } while (0)
; #define PG8_MMA(ai, bj, At, Bt) do { __builtin_amdgcn_s_setprio(1); _Pragma("unroll") for (int m = 0; m < 4; ++m) _Pragma("unroll") for (int n = 0; n < 2; ++n) _Pragma("unroll") for (int k = 0; k < 2; ++k) \
;         acc[ai][bj][m][n] = __builtin_amdgcn_mfma_f32_16x16x32_bf16(Bt[n][k], At[m][k], acc[ai][bj][m][n], 0, 0, 0); __builtin_amdgcn_s_setprio(0); } while (0)
; #define PG8_WAIT_V(n) asm volatile("s_waitcnt vmcnt(" #n ")" ::: "memory")
; #define PG8_WAIT_L(n) asm volatile("s_waitcnt lgkmcnt(" #n ")" ::: "memory")
; #define PG8_BAR __builtin_amdgcn_s_barrier()
; #define PG8_SCHED __builtin_amdgcn_sched_barrier(0)
; __device__ __forceinline__ void gemm_phase(PG8_LAS unsigned char* lds, const Gemm g, const StaticOrder& S, const Epi& E, const int tid) {
;     ...
;             PG8_LDA(At, 1, 1); PG8_STAGE(PG8_SB(1, 0), b3, voffB); PG8_STAGE(PG8_SB(1, 1), b3 + hstepB, voffB); PG8_STAGE(PG8_SA(1, 0), a3, voffA);
;             PG8_WAIT_V(8); PG8_WAIT_L(0); PG8_BAR; PG8_MMA(1, 0, At, B0); PG8_MMA(1, 1, At, B1); PG8_BAR; PG8_SCHED;
;         }
;         if (wr == 0) PG8_BAR;
	s_add_i32 s44, s68, s31
	v_lshl_add_u64 v[210:211], v[210:211], 0, s[36:37]
	s_mov_b32 m0, s44
	ds_read_b128 v[194:197], v188 offset:49152
	ds_read_b128 v[198:201], v188 offset:50176
	ds_read_b128 v[202:205], v188 offset:51200
	ds_read_b128 v[206:209], v188 offset:52224
	ds_read_b128 v[224:227], v188 offset:53248
	ds_read_b128 v[228:231], v188 offset:54272
	ds_read_b128 v[232:235], v188 offset:55296
	ds_read_b128 v[236:239], v188 offset:56320
	global_load_lds_dwordx4 v[210:211], off
	v_lshl_add_u64 v[210:211], v[240:241], 0, s[36:37]
	s_add_i32 m0, s44, 0x2000
	s_add_i32 s44, s69, s31
	global_load_lds_dwordx4 v[210:211], off
	v_lshl_add_u64 v[210:211], v[242:243], 0, s[36:37]
	s_mov_b32 m0, s44
	s_nop 0
	global_load_lds_dwordx4 v[210:211], off
	v_lshl_add_u64 v[210:211], v[244:245], 0, s[36:37]
	s_add_i32 m0, s44, 0x2000
	s_nop 0
	global_load_lds_dwordx4 v[210:211], off
	v_lshl_add_u64 v[210:211], v[246:247], 0, s[36:37]
	s_mov_b32 m0, s12
	s_nop 0
	global_load_lds_dwordx4 v[210:211], off
	v_lshl_add_u64 v[210:211], v[248:249], 0, s[36:37]
	s_mov_b32 m0, s13
	s_nop 0
	global_load_lds_dwordx4 v[210:211], off
	s_waitcnt vmcnt(8)
	s_waitcnt lgkmcnt(0)
	s_barrier
	s_setprio 1
	s_waitcnt lgkmcnt(0)
	v_mfma_f32_16x16x32_bf16 v[62:65], v[136:139], v[194:197], v[62:65]
	v_mfma_f32_16x16x32_bf16 v[58:61], v[156:159], v[194:197], v[58:61]
	v_mfma_f32_16x16x32_bf16 v[46:49], v[136:139], v[202:205], v[46:49]
	v_mfma_f32_16x16x32_bf16 v[42:45], v[156:159], v[202:205], v[42:45]
	v_mfma_f32_16x16x32_bf16 v[30:33], v[136:139], v[224:227], v[30:33]
	v_mfma_f32_16x16x32_bf16 v[26:29], v[156:159], v[224:227], v[26:29]
	v_mfma_f32_16x16x32_bf16 v[14:17], v[136:139], v[232:235], v[14:17]
	v_mfma_f32_16x16x32_bf16 v[10:13], v[156:159], v[232:235], v[10:13]
	v_mfma_f32_16x16x32_bf16 v[62:65], v[140:143], v[198:201], v[62:65]
	v_mfma_f32_16x16x32_bf16 v[58:61], v[160:163], v[198:201], v[58:61]
	v_mfma_f32_16x16x32_bf16 v[46:49], v[140:143], v[206:209], v[46:49]
	v_mfma_f32_16x16x32_bf16 v[42:45], v[160:163], v[206:209], v[42:45]
	v_mfma_f32_16x16x32_bf16 v[30:33], v[140:143], v[228:231], v[30:33]
	v_mfma_f32_16x16x32_bf16 v[26:29], v[160:163], v[228:231], v[26:29]
	v_mfma_f32_16x16x32_bf16 v[14:17], v[140:143], v[236:239], v[14:17]
	v_mfma_f32_16x16x32_bf16 v[10:13], v[160:163], v[236:239], v[10:13]
	s_setprio 0
	s_setprio 1
	v_mfma_f32_16x16x32_bf16 v[54:57], v[164:167], v[194:197], v[54:57]
	v_mfma_f32_16x16x32_bf16 v[50:53], v[172:175], v[194:197], v[50:53]
	v_mfma_f32_16x16x32_bf16 v[38:41], v[164:167], v[202:205], v[38:41]
	v_mfma_f32_16x16x32_bf16 v[34:37], v[172:175], v[202:205], v[34:37]
	v_mfma_f32_16x16x32_bf16 v[22:25], v[164:167], v[224:227], v[22:25]
	v_mfma_f32_16x16x32_bf16 v[18:21], v[172:175], v[224:227], v[18:21]
	v_mfma_f32_16x16x32_bf16 v[6:9], v[164:167], v[232:235], v[6:9]
	v_mfma_f32_16x16x32_bf16 v[2:5], v[172:175], v[232:235], v[2:5]
	v_mfma_f32_16x16x32_bf16 v[54:57], v[168:171], v[198:201], v[54:57]
	v_mfma_f32_16x16x32_bf16 v[50:53], v[190:193], v[198:201], v[50:53]
	v_mfma_f32_16x16x32_bf16 v[38:41], v[168:171], v[206:209], v[38:41]
	v_mfma_f32_16x16x32_bf16 v[34:37], v[190:193], v[206:209], v[34:37]
	v_mfma_f32_16x16x32_bf16 v[22:25], v[168:171], v[228:231], v[22:25]
	v_mfma_f32_16x16x32_bf16 v[18:21], v[190:193], v[228:231], v[18:21]
	v_mfma_f32_16x16x32_bf16 v[6:9], v[168:171], v[236:239], v[6:9]
	v_mfma_f32_16x16x32_bf16 v[2:5], v[190:193], v[236:239], v[2:5]
	s_setprio 0
	s_barrier
	s_add_u32 s10, s10, 0x100
	s_addc_u32 s11, s11, 0
	s_add_u32 s47, s47, 0x100
	s_addc_u32 s48, s48, 0
	s_cmp_ge_u32 s49, s14
	s_mov_b32 s44, s49
	s_cbranch_scc0 .LBB0_88
.Lk_peel_done:
	s_and_b64 vcc, exec, s[72:73]
	s_cbranch_vccz .LBB0_91
	s_barrier
